# P5 queue interleaved by work: 2 attention units per 3 conversion batches, big:small conversion batches 1:2, so conversion never saturates HBM and no conversion-only tail
# baseline (speedup 1.0000x reference)
; #define REFRESH_IDS() do { lane = fresh_lane(); tid = wave * 64 + lane; } while (0)
; __global__ void __launch_bounds__(NWAVES * 64, 2) fwd(Args args) {
;     ...
;             constexpr int NB64 = (NCB * 3) / 4, NB16 = (NCB - NB64) * 4;
;             const unsigned q = MISC[16]; if (q >= 512u + (DEFER_AT == 5 ? (unsigned)(NB64 + NB16) : 0u)) break;
;             if (tid == 0) { int z = 0; asm volatile("" : "+v"(z)); qpre = __hip_atomic_fetch_add(ctl + CW_AQ + z, 1u, __ATOMIC_RELAXED, __HIP_MEMORY_SCOPE_AGENT); }
;             REFRESH_IDS();
;     ...
;             const bool conv = DEFER_AT == 5 ? (q < 1024u ? (q & 1u) != 0u : true) : false; const int idx = DEFER_AT == 5 ? (q < 1024u ? (int)(q >> 1) : (int)(q - 512u)) : (int)q;
;     ...
;             const bool conv = q >= 512u; const int idx = conv ? (int)(q - 512u) : (int)q;
;     ...
;             const bool conv = q < (unsigned)NCB; const int idx = conv ? (int)q : (int)(q - (unsigned)NCB);
;     ...
;             if (!conv) attn_wg(PROJ, CONCAT, idx, L, tid, lane, wave);
;             else {
;                 const bool small = idx >= NB64; const int first = NI0 + (small ? NB64 * 64 + (idx - NB64) * 16 : idx * 64) + wave;
.LBB0_646:
	s_or_b64 exec, exec, s[6:7]
	v_mbcnt_lo_u32_b32 v168, -1, 0
	v_mbcnt_hi_u32_b32 v168, -1, v168
	v_add_u32_e32 v185, s9, v168
	s_cmpk_gt_u32 s25, 0x4ff
	s_cbranch_scc0 .Lq5_pat
	s_add_i32 s4, s25, 0xfffffe00
	s_branch .Lq5_c
.Lq5_pat:
	s_mul_i32 s4, s25, 0x3334
	s_lshr_b32 s4, s4, 16
	s_mul_i32 s5, s4, 5
	s_sub_i32 s5, s25, s5
	s_cmp_eq_u32 s5, 0
	s_cbranch_scc1 .Lq5_a0
	s_cmp_eq_u32 s5, 3
	s_cbranch_scc1 .Lq5_a1
	s_sub_i32 s5, s5, 1
	s_min_u32 s5, s5, 2
	s_mul_i32 s4, s4, 3
	s_add_i32 s4, s4, s5
.Lq5_c:
	s_cmpk_lt_u32 s4, 0x339
	s_cbranch_scc1 .Lq5_mix
	s_add_i32 s25, s4, 512
	s_branch .Lq5_conv
.Lq5_mix:
	s_mul_i32 s98, s4, 0x5556
	s_lshr_b32 s98, s98, 16
	s_mul_i32 s99, s98, 3
	s_sub_i32 s99, s4, s99
	s_cmp_eq_u32 s99, 0
	s_cbranch_scc0 .Lq5_small
	s_add_i32 s25, s98, 0x200
	s_branch .Lq5_conv
.Lq5_small:
	s_lshl_b32 s98, s98, 1
	s_add_i32 s98, s98, s99
	s_add_i32 s25, s98, 786
	s_branch .Lq5_conv
.Lq5_a1:
	s_lshl_b32 s25, s4, 1
	s_add_i32 s25, s25, 1
	s_branch .Lq5_attn
.Lq5_a0:
	s_lshl_b32 s25, s4, 1
	s_branch .Lq5_attn
